# G1 epilogue: full VMEM drain kept only for the gate tiles that load a bias; other tiles no longer wait for the prefetched next-unit tiles
# baseline (speedup 1.0000x reference)
.LBB0_820:
	v_lshl_add_u32 v0, s2, 8, v174
	v_mov_b32_e32 v164, v177
	s_and_b64 vcc, exec, s[24:25]
	s_cbranch_vccnz .Lg1_nodrain
	s_waitcnt vmcnt(0)
.Lg1_nodrain:
	v_pk_add_f32 v[144:145], v[144:145], v[48:49]
	v_pk_add_f32 v[142:143], v[142:143], v[46:47]
	v_pk_add_f32 v[140:141], v[140:141], v[44:45]
	v_pk_add_f32 v[138:139], v[138:139], v[42:43]
	s_mov_b64 s[26:27], -1
	s_and_b64 vcc, exec, s[24:25]
	s_cbranch_vccz .LBB0_827
	s_cmp_gt_i32 s3, 1
	s_cbranch_scc0 .LBB0_823
	s_mov_b32 s12, 0x3e000000
	v_pk_mul_f32 v[172:173], v[144:145], s[12:13] op_sel_hi:[1,0]
	v_pk_mul_f32 v[166:167], v[142:143], s[12:13] op_sel_hi:[1,0]
	v_pk_mul_f32 v[170:171], v[140:141], s[12:13] op_sel_hi:[1,0]
	v_pk_mul_f32 v[168:169], v[138:139], s[12:13] op_sel_hi:[1,0]
	s_mov_b64 s[26:27], 0
